# speedup vs baseline: 1.0189x; 1.0189x over previous
.LBB0_85:
	v_mov_b32_e32 v40, v240
	v_mov_b64_e32 v[0:1], s[64:65]
	v_readfirstlane_b32 s17, v40
	s_ashr_i32 s19, s17, 6
	s_and_b32 s18, s19, 3
	s_lshl_b32 s10, s18, 5
	v_and_b32_e32 v6, 31, v40
	s_add_i32 s10, s10, s5
	v_add_u32_e32 v194, s10, v6
	s_movk_i32 s5, 0x5800
	s_lshl_b32 s3, s3, 7
	s_ashr_i32 s20, s17, 8
	v_mad_i64_i32 v[196:197], s[10:11], v194, s5, v[0:1]
	s_and_b32 s3, s3, 0x380
	s_lshl_b32 s90, s3, 1
	s_lshl_b32 s10, s20, 6
	v_bfe_u32 v41, v40, 5, 1
	v_lshl_add_u64 v[2:3], v[196:197], 0, s[90:91]
	s_ashr_i32 s11, s10, 31
	v_lshl_add_u64 v[2:3], s[10:11], 1, v[2:3]
	v_lshlrev_b32_e32 v128, 4, v41
	v_lshl_add_u64 v[2:3], v[2:3], 0, v[128:129]
	global_load_dwordx4 v[130:133], v[2:3], off
	global_load_dwordx4 v[134:137], v[2:3], off offset:32
	global_load_dwordx4 v[138:141], v[2:3], off offset:64
	global_load_dwordx4 v[142:145], v[2:3], off offset:96
	v_bfe_u32 v2, v40, 3, 3
	v_lshl_or_b32 v2, s19, 3, v2
	v_mad_i64_i32 v[0:1], s[10:11], v2, s5, v[0:1]
	v_lshrrev_b32_e32 v3, 1, v2
	s_and_b32 s10, s19, 1
	v_bfe_u32 v2, v40, 2, 4
	v_lshlrev_b32_e32 v6, 7, v6
	v_lshl_or_b32 v2, s10, 5, v2
	v_lshl_or_b32 v43, s20, 13, v6
	v_lshrrev_b32_e32 v6, 1, v40
	v_xor_b32_e32 v7, v3, v40
	v_mul_u32_u24_e32 v2, 0x2c00, v2
	v_bitop3_b32 v6, v41, v6, 7 bitop3:0x78
	v_lshlrev_b32_e32 v128, 1, v2
	v_lshlrev_b32_e32 v4, 3, v40
	v_lshl_or_b32 v204, v6, 4, v43
	v_lshlrev_b32_e32 v6, 4, v7
	s_ashr_i32 s11, s17, 7
	v_lshl_add_u64 v[2:3], s[64:65], 0, v[128:129]
	v_and_b32_e32 v42, 24, v4
	v_lshl_add_u64 v[0:1], v[0:1], 0, s[90:91]
	v_and_b32_e32 v128, 0x70, v6
	v_lshl_or_b32 v4, s11, 5, v42
	s_lshl_b32 s5, s19, 10
	s_lshl_b32 s10, s10, 11
	s_lshl_b32 s11, s11, 12
	v_lshl_add_u64 v[198:199], v[0:1], 0, v[128:129]
	v_lshl_add_u64 v[0:1], v[198:199], 0, s[72:73]
	s_or_b32 s24, s10, s11
	s_add_i32 s19, s5, 0
	s_mov_b32 s10, m0
	s_mov_b32 m0, s19
	s_nop 0
	global_load_lds_dwordx4 v[0:1], off
	s_mov_b32 m0, s10
	v_lshl_add_u64 v[0:1], v[198:199], 0, s[94:95]
	s_add_i32 s21, s19, 0x2000
	s_mov_b32 s10, m0
	s_mov_b32 m0, s21
	s_nop 0
	global_load_lds_dwordx4 v[0:1], off
	s_mov_b32 m0, s10
	s_mov_b64 s[10:11], 0x160800
	v_lshl_add_u64 v[0:1], v[198:199], 0, s[10:11]
	s_add_i32 s10, s19, 0x4000
	s_mov_b32 s11, m0
	s_mov_b32 m0, s10
	s_nop 0
	global_load_lds_dwordx4 v[0:1], off
	s_mov_b32 m0, s11
	s_mov_b64 s[10:11], 0x160880
	v_lshl_add_u64 v[0:1], v[198:199], 0, s[10:11]
	s_add_i32 s10, s19, 0x6000
	s_mov_b32 s11, m0
	s_mov_b32 m0, s10
	s_nop 0
	global_load_lds_dwordx4 v[0:1], off
	s_mov_b32 m0, s11
	s_mov_b64 s[10:11], 0x2c0800
	v_lshl_add_u64 v[0:1], v[198:199], 0, s[10:11]
	s_add_i32 s10, s19, 0x8000
	s_mov_b32 s11, m0
	s_mov_b32 m0, s10
	s_nop 0
	global_load_lds_dwordx4 v[0:1], off
	s_mov_b32 m0, s11
	v_ashrrev_i32_e32 v5, 31, v4
	v_lshl_add_u64 v[2:3], v[2:3], 0, s[90:91]
	s_mov_b64 s[10:11], 0x2c0880
	v_lshl_add_u64 v[2:3], v[4:5], 1, v[2:3]
	v_lshl_add_u64 v[0:1], v[198:199], 0, s[10:11]
	s_add_i32 s10, s19, 0xa000
	s_mov_b32 s11, m0
	s_mov_b32 m0, s10
	s_nop 0
	global_load_lds_dwordx4 v[0:1], off
	s_mov_b32 m0, s11
	s_add_i32 s20, s24, 0
	v_lshl_add_u64 v[200:201], v[2:3], 0, s[98:99]
	s_add_i32 s10, s20, 0xc000
	s_mov_b32 s11, m0
	s_mov_b32 m0, s10
	s_nop 0
	global_load_lds_dwordx4 v[200:201], off
	s_mov_b32 m0, s11
	s_mov_b64 s[10:11], 0x59000
	v_lshl_add_u64 v[0:1], v[2:3], 0, s[10:11]
	s_add_i32 s10, s20, 0xc400
	s_mov_b32 s11, m0
	s_mov_b32 m0, s10
	s_nop 0
	global_load_lds_dwordx4 v[0:1], off
	s_mov_b32 m0, s11
	s_mov_b64 s[10:11], 0x161000
	v_lshl_add_u64 v[0:1], v[2:3], 0, s[10:11]
	s_add_i32 s10, s20, 0x10000
	s_mov_b32 s11, m0
	s_mov_b32 m0, s10
	s_nop 0
	global_load_lds_dwordx4 v[0:1], off
	s_mov_b32 m0, s11
	s_mov_b64 s[10:11], 0x1b9000
	v_lshl_add_u64 v[0:1], v[2:3], 0, s[10:11]
	s_add_i32 s20, s20, 0x10400
	s_mov_b32 s10, m0
	s_mov_b32 m0, s20
	s_nop 0
	global_load_lds_dwordx4 v[0:1], off
	s_mov_b32 m0, s10
	s_waitcnt vmcnt(0)
	s_barrier
	v_add_u32_e32 v44, 0, v204
	ds_read_b128 v[0:3], v44
	ds_read_b128 v[4:7], v44 offset:4096
	s_waitcnt vmcnt(3) lgkmcnt(1)
	v_mfma_f32_32x32x16_bf16 v[16:31], v[0:3], v[130:133], 0
	v_bfe_u32 v45, v40, 1, 3
	v_bitop3_b32 v0, v41, v45, 2 bitop3:0x36
	v_lshl_or_b32 v128, v0, 4, v43
	v_add_u32_e32 v46, 0, v128
	ds_read_b128 v[32:35], v46
	ds_read_b128 v[36:39], v46 offset:4096
	v_lshlrev_b32_e32 v203, 2, v41
	s_mov_b64 s[22:23], 0x420800
	s_waitcnt lgkmcnt(2)
	v_mfma_f32_32x32x16_bf16 v[0:15], v[4:7], v[130:133], 0
	v_mov_b32_e32 v209, 0
	v_and_b32_e32 v202, 63, v40
	v_ashrrev_i32_e32 v195, 31, v194
	s_movk_i32 s10, 0x4000
	s_mov_b32 s11, 0x8000
	s_mov_b32 s20, 0
	s_mov_b32 s33, 0
	s_waitcnt vmcnt(2) lgkmcnt(1)
	v_mfma_f32_32x32x16_bf16 v[16:31], v[32:35], v[134:137], v[16:31]
	v_bitop3_b32 v32, v41, v45, 4 bitop3:0x36
	v_lshl_or_b32 v205, v32, 4, v43
	v_add_u32_e32 v47, 0, v205
	v_mov_b32_e32 v48, 0
	v_mov_b32_e32 v49, v209
	v_mov_b32_e32 v50, v209
	v_mov_b32_e32 v51, v209
	s_waitcnt lgkmcnt(0)
	v_mfma_f32_32x32x16_bf16 v[0:15], v[36:39], v[134:137], v[0:15]
	ds_read_b128 v[32:35], v47
	ds_read_b128 v[36:39], v47 offset:4096
	v_mov_b32_e32 v52, v209
	v_mov_b32_e32 v53, v209
	v_mov_b32_e32 v54, v209
	v_mov_b32_e32 v55, v209
	v_mov_b32_e32 v56, v209
	v_mov_b32_e32 v57, v209
	s_waitcnt vmcnt(1) lgkmcnt(1)
	v_mfma_f32_32x32x16_bf16 v[16:31], v[32:35], v[138:141], v[16:31]
	v_bitop3_b32 v32, v41, v45, 6 bitop3:0x36
	v_lshl_or_b32 v206, v32, 4, v43
	v_add_u32_e32 v43, 0, v206
	ds_read_b128 v[32:35], v43
	v_mov_b32_e32 v45, v209
	v_mov_b32_e32 v58, v209
	v_mov_b32_e32 v59, v209
	s_waitcnt lgkmcnt(1)
	v_mfma_f32_32x32x16_bf16 v[0:15], v[36:39], v[138:141], v[0:15]
	v_lshrrev_b32_e32 v36, 2, v40
	v_and_or_b32 v41, v36, 3, v203
	ds_read_b128 v[36:39], v43 offset:4096
	ds_read_b128 v[100:103], v44 offset:16384
	ds_read_b128 v[96:99], v44 offset:20480
	ds_read_b128 v[182:185], v46 offset:16384
	ds_read_b128 v[178:181], v46 offset:20480
	ds_read_b128 v[174:177], v47 offset:16384
	ds_read_b128 v[170:173], v47 offset:20480
	ds_read_b128 v[166:169], v43 offset:16384
	ds_read_b128 v[162:165], v43 offset:20480
	s_waitcnt lgkmcnt(0)
	s_barrier
	v_mov_b32_e32 v43, v209
	v_mov_b32_e32 v44, v209
	s_waitcnt vmcnt(0) lgkmcnt(9)
	v_mfma_f32_32x32x16_bf16 v[16:31], v[32:35], v[142:145], v[16:31]
	v_lshlrev_b32_e32 v33, 1, v40
	v_lshlrev_b32_e32 v32, 6, v41
	v_and_b32_e32 v33, 32, v33
	v_or3_b32 v207, v32, v33, v42
	v_lshl_add_u64 v[32:33], v[198:199], 0, s[22:23]
	s_mov_b32 s22, m0
	s_mov_b32 m0, s19
	s_nop 0
	global_load_lds_dwordx4 v[32:33], off
	s_mov_b32 m0, s22
	s_mov_b64 s[22:23], 0x420880
	s_waitcnt lgkmcnt(8)
	v_mfma_f32_32x32x16_bf16 v[0:15], v[36:39], v[142:145], v[0:15]
	s_nop 3
	v_exp_f32_e32 v80, v16
	v_exp_f32_e32 v81, v17
	v_exp_f32_e32 v82, v18
	v_exp_f32_e32 v83, v19
	v_exp_f32_e32 v84, v20
	v_exp_f32_e32 v85, v21
	v_exp_f32_e32 v86, v22
	v_exp_f32_e32 v87, v23
	v_exp_f32_e32 v88, v24
	v_exp_f32_e32 v89, v25
	v_exp_f32_e32 v90, v26
	v_exp_f32_e32 v91, v27
	v_exp_f32_e32 v92, v28
	v_exp_f32_e32 v93, v29
	v_exp_f32_e32 v94, v30
	v_exp_f32_e32 v95, v31
	v_exp_f32_e32 v64, v0
	v_exp_f32_e32 v65, v1
	v_exp_f32_e32 v66, v2
	v_exp_f32_e32 v67, v3
	v_exp_f32_e32 v68, v4
	v_exp_f32_e32 v69, v5
	v_exp_f32_e32 v70, v6
	v_exp_f32_e32 v71, v7
	v_exp_f32_e32 v72, v8
	v_exp_f32_e32 v73, v9
	v_exp_f32_e32 v74, v10
	v_exp_f32_e32 v75, v11
	v_exp_f32_e32 v76, v12
	v_exp_f32_e32 v77, v13
	v_exp_f32_e32 v78, v14
	v_exp_f32_e32 v79, v15
	v_lshl_add_u64 v[32:33], v[198:199], 0, s[22:23]
	s_mov_b32 s19, m0
	s_mov_b32 m0, s21
	s_nop 0
	global_load_lds_dwordx4 v[32:33], off
	s_mov_b32 m0, s19
	v_add_u32_e32 v208, 0, v207
	s_add_i32 s19, s4, -1
	s_add_i32 s21, s5, 0x2000
	s_add_i32 s22, s24, 0xc000
	v_mov_b32_e32 v0, 0
	v_mov_b32_e32 v1, v209
	v_mov_b32_e32 v2, v209
	v_mov_b32_e32 v3, v209
	v_mov_b32_e32 v4, v209
	v_mov_b32_e32 v5, v209
	v_mov_b32_e32 v6, v209
	v_mov_b32_e32 v7, v209
	v_mov_b32_e32 v8, v209
	v_mov_b32_e32 v9, v209
	v_mov_b32_e32 v10, v209
	v_mov_b32_e32 v11, v209
	v_mov_b32_e32 v12, v209
	v_mov_b32_e32 v13, v209
	v_mov_b32_e32 v14, v209
	v_mov_b32_e32 v15, v209
	v_mov_b32_e32 v16, 0
	v_mov_b32_e32 v17, v209
	v_mov_b32_e32 v18, v209
	v_mov_b32_e32 v19, v209
	v_mov_b32_e32 v20, v209
	v_mov_b32_e32 v21, v209
	v_mov_b32_e32 v22, v209
	v_mov_b32_e32 v23, v209
	v_mov_b32_e32 v24, v209
	v_mov_b32_e32 v25, v209
	v_mov_b32_e32 v26, v209
	v_mov_b32_e32 v27, v209
	v_mov_b32_e32 v28, v209
	v_mov_b32_e32 v29, v209
	v_mov_b32_e32 v30, v209
	v_mov_b32_e32 v31, v209
	v_mov_b32_e32 v32, 0
	v_mov_b32_e32 v33, v209
	v_mov_b32_e32 v34, v209
	v_mov_b32_e32 v35, v209
	v_mov_b32_e32 v36, v209
	v_mov_b32_e32 v37, v209
	v_mov_b32_e32 v38, v209
	v_mov_b32_e32 v39, v209
	v_mov_b32_e32 v40, v209
	v_mov_b32_e32 v41, v209
	v_mov_b32_e32 v42, v209
	v_mov_b32_e32 v46, v209
	v_mov_b32_e32 v47, v209
	v_mov_b32_e32 v60, v209
	v_mov_b32_e32 v61, v209
	v_mov_b32_e32 v62, v209
	v_mov_b32_e32 v63, v209
	v_readfirstlane_b32 s44, v198
	v_readfirstlane_b32 s45, v199
	s_nop 1
	s_sub_u32 s44, s44, 0x200000
	s_subb_u32 s45, s45, 0
	s_add_i32 s32, s21, 0xffffff80
	v_subrev_u32_e32 v199, s44, v198
	v_add_u32_e32 v199, 0x800, v199
	v_subrev_u32_e32 v201, s44, v200
.LBB0_86:
	s_mov_b32 s23, s10
	s_mov_b32 s10, s20
	s_add_i32 s24, s33, 2
	s_add_i32 s25, s10, 0
	v_add_u32_e32 v210, s25, v207
	v_mfma_f32_32x32x16_bf16 v[112:127], v[100:103], v[130:133], 0
	v_add_f32_e32 v100, 0, v80
	v_add_f32_e32 v101, 0, v81
	v_add_f32_e32 v100, v82, v100
	v_add_f32_e32 v101, v83, v101
	v_cvt_pk_bf16_f32 v158, v80, v81
	v_cvt_pk_bf16_f32 v159, v82, v83
	v_add_f32_e32 v80, v84, v100
	v_add_f32_e32 v81, v85, v101
	v_add_f32_e32 v146, v86, v80
	v_cvt_pk_bf16_f32 v160, v84, v85
	v_mfma_f32_32x32x16_bf16 v[96:111], v[96:99], v[130:133], 0
	v_add_f32_e32 v84, v87, v81
	v_cvt_pk_bf16_f32 v161, v86, v87
	ds_read_b64_tr_b16 v[80:81], v210 offset:49152
	ds_read_b64_tr_b16 v[82:83], v210 offset:49664
	v_add_f32_e32 v85, v88, v146
	v_add_f32_e32 v84, v89, v84
	v_mfma_f32_32x32x16_bf16 v[112:127], v[182:185], v[134:137], v[112:127]
	v_add_f32_e32 v146, v90, v85
	v_add_f32_e32 v147, v91, v84
	v_cvt_pk_bf16_f32 v154, v88, v89
	v_cvt_pk_bf16_f32 v155, v90, v91
	ds_read_b64_tr_b16 v[84:85], v210 offset:53248
	ds_read_b64_tr_b16 v[86:87], v210 offset:53760
	v_add_f32_e32 v88, v92, v146
	v_add_f32_e32 v89, v93, v147
	v_mfma_f32_32x32x16_bf16 v[96:111], v[178:181], v[134:137], v[96:111]
	v_add_f32_e32 v146, v94, v88
	v_add_f32_e32 v147, v95, v89
	v_cvt_pk_bf16_f32 v156, v92, v93
	v_cvt_pk_bf16_f32 v157, v94, v95
	ds_read_b64_tr_b16 v[88:89], v210 offset:57344
	ds_read_b64_tr_b16 v[90:91], v210 offset:57856
	v_add_f32_e32 v92, v64, v146
	v_add_f32_e32 v93, v65, v147
	v_mfma_f32_32x32x16_bf16 v[112:127], v[174:177], v[138:141], v[112:127]
	v_add_f32_e32 v92, v66, v92
	v_add_f32_e32 v93, v67, v93
	v_cvt_pk_bf16_f32 v150, v64, v65
	v_cvt_pk_bf16_f32 v151, v66, v67
	ds_read_b64_tr_b16 v[64:65], v210 offset:61440
	ds_read_b64_tr_b16 v[66:67], v210 offset:61952
	v_add_f32_e32 v92, v68, v92
	v_add_f32_e32 v93, v69, v93
	v_mfma_f32_32x32x16_bf16 v[96:111], v[170:173], v[138:141], v[96:111]
	v_add_f32_e32 v92, v70, v92
	v_add_f32_e32 v93, v71, v93
	v_cvt_pk_bf16_f32 v152, v68, v69
	v_cvt_pk_bf16_f32 v153, v70, v71
	v_add_f32_e32 v68, v72, v92
	v_add_f32_e32 v69, v73, v93
	v_mfma_f32_32x32x16_bf16 v[112:127], v[166:169], v[142:145], v[112:127]
	v_add_f32_e32 v68, v74, v68
	v_add_f32_e32 v69, v75, v69
	v_cvt_pk_bf16_f32 v146, v72, v73
	v_cvt_pk_bf16_f32 v147, v74, v75
	v_add_f32_e32 v68, v76, v68
	v_add_f32_e32 v69, v77, v69
	v_mfma_f32_32x32x16_bf16 v[96:111], v[162:165], v[142:145], v[96:111]
	v_add_f32_e32 v68, v78, v68
	v_add_f32_e32 v69, v79, v69
	v_cvt_pk_bf16_f32 v148, v76, v77
	v_cvt_pk_bf16_f32 v149, v78, v79
	s_nop 0
	v_exp_f32_e32 v112, v112
	v_exp_f32_e32 v113, v113
	s_waitcnt lgkmcnt(4)
	v_mfma_f32_32x32x16_bf16 v[48:63], v[80:83], v[158:161], v[48:63]
	v_add_f32_e32 v92, v68, v69
	ds_read_b64_tr_b16 v[68:69], v210 offset:50176
	ds_read_b64_tr_b16 v[70:71], v210 offset:50688
	v_exp_f32_e32 v114, v114
	v_exp_f32_e32 v115, v115
	v_mfma_f32_32x32x16_bf16 v[32:47], v[84:87], v[158:161], v[32:47]
	ds_read_b64_tr_b16 v[72:73], v210 offset:54272
	ds_read_b64_tr_b16 v[74:75], v210 offset:54784
	v_exp_f32_e32 v116, v116
	v_exp_f32_e32 v117, v117
	s_waitcnt lgkmcnt(4)
	v_mfma_f32_32x32x16_bf16 v[16:31], v[88:91], v[158:161], v[16:31]
	s_add_i32 s90, s33, 4
	s_min_u32 s90, s90, s19
	s_mul_i32 s90, s90, 0x160000
	s_add_i32 m0, s23, s5
	s_add_u32 s100, s44, s90
	s_addc_u32 s101, s45, 0
	global_load_lds_dwordx4 v199, s[100:101]
	ds_read_b64_tr_b16 v[76:77], v210 offset:58368
	ds_read_b64_tr_b16 v[78:79], v210 offset:58880
	v_exp_f32_e32 v118, v118
	v_exp_f32_e32 v119, v119
	v_mfma_f32_32x32x16_bf16 v[0:15], v[64:67], v[158:161], v[0:15]
	ds_read_b64_tr_b16 v[80:81], v210 offset:62464
	ds_read_b64_tr_b16 v[82:83], v210 offset:62976
	v_exp_f32_e32 v120, v120
	v_exp_f32_e32 v121, v121
	s_waitcnt lgkmcnt(4)
	v_mfma_f32_32x32x16_bf16 v[48:63], v[68:71], v[154:157], v[48:63]
	v_add_u32_e32 v64, s11, v204
	ds_read_b64_tr_b16 v[84:85], v210 offset:51200
	ds_read_b64_tr_b16 v[86:87], v210 offset:51712
	ds_read_b128 v[68:71], v64
	v_exp_f32_e32 v122, v122
	v_exp_f32_e32 v123, v123
	v_mfma_f32_32x32x16_bf16 v[32:47], v[72:75], v[154:157], v[32:47]
	ds_read_b64_tr_b16 v[72:73], v210 offset:55296
	ds_read_b64_tr_b16 v[74:75], v210 offset:55808
	ds_read_b128 v[64:67], v64 offset:4096
	v_exp_f32_e32 v124, v124
	v_exp_f32_e32 v125, v125
	s_waitcnt lgkmcnt(6)
	v_mfma_f32_32x32x16_bf16 v[16:31], v[76:79], v[154:157], v[16:31]
	s_add_i32 m0, s23, s32
	s_nop 0
	global_load_lds_dwordx4 v199, s[100:101] offset:128
	v_add_u32_e32 v88, s11, v128
	ds_read_b64_tr_b16 v[76:77], v210 offset:59392
	ds_read_b64_tr_b16 v[78:79], v210 offset:59904
	ds_read_b128 v[182:185], v88
	v_exp_f32_e32 v126, v126
	v_exp_f32_e32 v127, v127
	v_mfma_f32_32x32x16_bf16 v[0:15], v[80:83], v[154:157], v[0:15]
	ds_read_b64_tr_b16 v[80:81], v210 offset:63488
	ds_read_b64_tr_b16 v[82:83], v210 offset:64000
	ds_read_b128 v[178:181], v88 offset:4096
	v_exp_f32_e32 v96, v96
	v_exp_f32_e32 v97, v97
	s_waitcnt lgkmcnt(7)
	v_mfma_f32_32x32x16_bf16 v[48:63], v[84:87], v[150:153], v[48:63]
	v_add_u32_e32 v88, s11, v205
	ds_read_b64_tr_b16 v[84:85], v210 offset:52224
	ds_read_b64_tr_b16 v[86:87], v210 offset:52736
	ds_read_b128 v[174:177], v88
	v_exp_f32_e32 v98, v98
	v_exp_f32_e32 v99, v99
	v_mfma_f32_32x32x16_bf16 v[32:47], v[72:75], v[150:153], v[32:47]
	ds_read_b64_tr_b16 v[72:73], v210 offset:56320
	ds_read_b64_tr_b16 v[74:75], v210 offset:56832
	ds_read_b128 v[170:173], v88 offset:4096
	v_exp_f32_e32 v100, v100
	v_exp_f32_e32 v101, v101
	s_waitcnt lgkmcnt(7)
	v_mfma_f32_32x32x16_bf16 v[16:31], v[76:79], v[150:153], v[16:31]
	s_min_u32 s90, s24, s19
	s_mul_i32 s90, s90, 0x160000
	s_add_i32 m0, s11, s22
	s_add_u32 s100, s44, s90
	s_addc_u32 s101, s45, 0
	global_load_lds_dwordx4 v201, s[100:101]
	v_add_u32_e32 v88, s11, v206
	ds_read_b64_tr_b16 v[76:77], v210 offset:60416
	ds_read_b64_tr_b16 v[78:79], v210 offset:60928
	ds_read_b128 v[166:169], v88
	v_exp_f32_e32 v102, v102
	v_exp_f32_e32 v103, v103
	v_mfma_f32_32x32x16_bf16 v[0:15], v[80:83], v[150:153], v[0:15]
	ds_read_b64_tr_b16 v[80:81], v210 offset:64512
	ds_read_b64_tr_b16 v[82:83], v210 offset:65024
	ds_read_b128 v[162:165], v88 offset:4096
	v_exp_f32_e32 v104, v104
	v_exp_f32_e32 v105, v105
	s_waitcnt lgkmcnt(7)
	v_mfma_f32_32x32x16_bf16 v[48:63], v[84:87], v[146:149], v[48:63]
	v_exp_f32_e32 v106, v106
	v_exp_f32_e32 v107, v107
	v_mfma_f32_32x32x16_bf16 v[32:47], v[72:75], v[146:149], v[32:47]
	v_exp_f32_e32 v108, v108
	v_exp_f32_e32 v109, v109
	s_waitcnt lgkmcnt(1)
	v_mfma_f32_32x32x16_bf16 v[16:31], v[76:79], v[146:149], v[16:31]
	s_add_i32 m0, s11, s22
	s_addk_i32 m0, 0x400
	s_add_u32 s100, s100, 0x58000
	s_addc_u32 s101, s101, 0
	global_load_lds_dwordx4 v201, s[100:101]
	v_exp_f32_e32 v110, v110
	v_exp_f32_e32 v111, v111
	v_mfma_f32_32x32x16_bf16 v[0:15], v[80:83], v[146:149], v[0:15]
	s_waitcnt vmcnt(4) lgkmcnt(0)
	s_barrier
	v_add_f32_e32 v186, v209, v92
	v_add_u32_e32 v210, s23, v208
	v_mfma_f32_32x32x16_bf16 v[80:95], v[68:71], v[130:133], 0
	v_add_f32_e32 v68, 0, v112
	v_add_f32_e32 v69, 0, v113
	v_add_f32_e32 v68, v114, v68
	v_add_f32_e32 v69, v115, v69
	v_cvt_pk_bf16_f32 v158, v112, v113
	v_cvt_pk_bf16_f32 v159, v114, v115
	v_add_f32_e32 v68, v116, v68
	v_add_f32_e32 v112, v117, v69
	v_add_f32_e32 v146, v118, v68
	v_cvt_pk_bf16_f32 v160, v116, v117
	v_mfma_f32_32x32x16_bf16 v[64:79], v[64:67], v[130:133], 0
	v_add_f32_e32 v116, v119, v112
	v_cvt_pk_bf16_f32 v161, v118, v119
	ds_read_b64_tr_b16 v[112:113], v210 offset:49152
	ds_read_b64_tr_b16 v[114:115], v210 offset:49664
	v_add_f32_e32 v117, v120, v146
	v_add_f32_e32 v116, v121, v116
	v_mfma_f32_32x32x16_bf16 v[80:95], v[182:185], v[134:137], v[80:95]
	v_add_f32_e32 v146, v122, v117
	v_add_f32_e32 v147, v123, v116
	v_cvt_pk_bf16_f32 v154, v120, v121
	v_cvt_pk_bf16_f32 v155, v122, v123
	ds_read_b64_tr_b16 v[116:117], v210 offset:53248
	ds_read_b64_tr_b16 v[118:119], v210 offset:53760
	v_add_f32_e32 v120, v124, v146
	v_add_f32_e32 v121, v125, v147
	v_mfma_f32_32x32x16_bf16 v[64:79], v[178:181], v[134:137], v[64:79]
	v_add_f32_e32 v146, v126, v120
	v_add_f32_e32 v147, v127, v121
	v_cvt_pk_bf16_f32 v156, v124, v125
	v_cvt_pk_bf16_f32 v157, v126, v127
	ds_read_b64_tr_b16 v[120:121], v210 offset:57344
	ds_read_b64_tr_b16 v[122:123], v210 offset:57856
	v_add_f32_e32 v124, v96, v146
	v_add_f32_e32 v125, v97, v147
	v_mfma_f32_32x32x16_bf16 v[80:95], v[174:177], v[138:141], v[80:95]
	v_add_f32_e32 v124, v98, v124
	v_add_f32_e32 v125, v99, v125
	v_cvt_pk_bf16_f32 v150, v96, v97
	v_cvt_pk_bf16_f32 v151, v98, v99
	ds_read_b64_tr_b16 v[96:97], v210 offset:61440
	ds_read_b64_tr_b16 v[98:99], v210 offset:61952
	v_add_f32_e32 v124, v100, v124
	v_add_f32_e32 v125, v101, v125
	v_mfma_f32_32x32x16_bf16 v[64:79], v[170:173], v[138:141], v[64:79]
	v_add_f32_e32 v124, v102, v124
	v_add_f32_e32 v125, v103, v125
	v_cvt_pk_bf16_f32 v152, v100, v101
	v_cvt_pk_bf16_f32 v153, v102, v103
	v_add_f32_e32 v100, v104, v124
	v_add_f32_e32 v101, v105, v125
	v_mfma_f32_32x32x16_bf16 v[80:95], v[166:169], v[142:145], v[80:95]
	v_add_f32_e32 v100, v106, v100
	v_add_f32_e32 v101, v107, v101
	v_cvt_pk_bf16_f32 v146, v104, v105
	v_cvt_pk_bf16_f32 v147, v106, v107
	v_add_f32_e32 v100, v108, v100
	v_add_f32_e32 v101, v109, v101
	v_mfma_f32_32x32x16_bf16 v[64:79], v[162:165], v[142:145], v[64:79]
	v_add_f32_e32 v100, v110, v100
	v_add_f32_e32 v101, v111, v101
	v_cvt_pk_bf16_f32 v148, v108, v109
	v_cvt_pk_bf16_f32 v149, v110, v111
	v_add_f32_e32 v100, v100, v101
	v_exp_f32_e32 v80, v80
	v_exp_f32_e32 v81, v81
	s_waitcnt lgkmcnt(4)
	v_mfma_f32_32x32x16_bf16 v[48:63], v[112:115], v[158:161], v[48:63]
	v_add_f32_e32 v209, v186, v100
	ds_read_b64_tr_b16 v[100:101], v210 offset:50176
	ds_read_b64_tr_b16 v[102:103], v210 offset:50688
	v_exp_f32_e32 v82, v82
	v_exp_f32_e32 v83, v83
	v_mfma_f32_32x32x16_bf16 v[32:47], v[116:119], v[158:161], v[32:47]
	ds_read_b64_tr_b16 v[104:105], v210 offset:54272
	ds_read_b64_tr_b16 v[106:107], v210 offset:54784
	v_exp_f32_e32 v84, v84
	v_exp_f32_e32 v85, v85
	s_waitcnt lgkmcnt(4)
	v_mfma_f32_32x32x16_bf16 v[16:31], v[120:123], v[158:161], v[16:31]
	s_add_i32 s90, s33, 5
	s_min_u32 s90, s90, s19
	s_mul_i32 s90, s90, 0x160000
	s_add_i32 m0, s11, s5
	s_add_u32 s100, s44, s90
	s_addc_u32 s101, s45, 0
	global_load_lds_dwordx4 v199, s[100:101]
	ds_read_b64_tr_b16 v[108:109], v210 offset:58368
	ds_read_b64_tr_b16 v[110:111], v210 offset:58880
	v_exp_f32_e32 v86, v86
	v_exp_f32_e32 v87, v87
	v_mfma_f32_32x32x16_bf16 v[0:15], v[96:99], v[158:161], v[0:15]
	ds_read_b64_tr_b16 v[112:113], v210 offset:62464
	ds_read_b64_tr_b16 v[114:115], v210 offset:62976
	v_exp_f32_e32 v88, v88
	v_exp_f32_e32 v89, v89
	s_waitcnt lgkmcnt(4)
	v_mfma_f32_32x32x16_bf16 v[48:63], v[100:103], v[154:157], v[48:63]
	v_add_u32_e32 v96, s25, v204
	ds_read_b64_tr_b16 v[116:117], v210 offset:51200
	ds_read_b64_tr_b16 v[118:119], v210 offset:51712
	ds_read_b128 v[100:103], v96
	v_exp_f32_e32 v90, v90
	v_exp_f32_e32 v91, v91
	v_mfma_f32_32x32x16_bf16 v[32:47], v[104:107], v[154:157], v[32:47]
	ds_read_b64_tr_b16 v[104:105], v210 offset:55296
	ds_read_b64_tr_b16 v[106:107], v210 offset:55808
	ds_read_b128 v[96:99], v96 offset:4096
	v_exp_f32_e32 v92, v92
	v_exp_f32_e32 v93, v93
	s_waitcnt lgkmcnt(6)
	v_mfma_f32_32x32x16_bf16 v[16:31], v[108:111], v[154:157], v[16:31]
	s_add_i32 m0, s11, s32
	s_nop 0
	global_load_lds_dwordx4 v199, s[100:101] offset:128
	v_add_u32_e32 v120, s25, v128
	ds_read_b64_tr_b16 v[108:109], v210 offset:59392
	ds_read_b64_tr_b16 v[110:111], v210 offset:59904
	ds_read_b128 v[182:185], v120
	v_exp_f32_e32 v94, v94
	v_exp_f32_e32 v95, v95
	v_mfma_f32_32x32x16_bf16 v[0:15], v[112:115], v[154:157], v[0:15]
	ds_read_b64_tr_b16 v[112:113], v210 offset:63488
	ds_read_b64_tr_b16 v[114:115], v210 offset:64000
	ds_read_b128 v[178:181], v120 offset:4096
	v_exp_f32_e32 v64, v64
	v_exp_f32_e32 v65, v65
	s_waitcnt lgkmcnt(7)
	v_mfma_f32_32x32x16_bf16 v[48:63], v[116:119], v[150:153], v[48:63]
	v_add_u32_e32 v120, s25, v205
	ds_read_b64_tr_b16 v[116:117], v210 offset:52224
	ds_read_b64_tr_b16 v[118:119], v210 offset:52736
	ds_read_b128 v[174:177], v120
	v_exp_f32_e32 v66, v66
	v_exp_f32_e32 v67, v67
	v_mfma_f32_32x32x16_bf16 v[32:47], v[104:107], v[150:153], v[32:47]
	ds_read_b64_tr_b16 v[104:105], v210 offset:56320
	ds_read_b64_tr_b16 v[106:107], v210 offset:56832
	ds_read_b128 v[170:173], v120 offset:4096
	v_exp_f32_e32 v68, v68
	v_exp_f32_e32 v69, v69
	s_waitcnt lgkmcnt(7)
	v_mfma_f32_32x32x16_bf16 v[16:31], v[108:111], v[150:153], v[16:31]
	s_add_i32 s90, s33, 3
	s_min_u32 s90, s90, s19
	s_mul_i32 s90, s90, 0x160000
	s_add_i32 m0, s10, s22
	s_add_u32 s100, s44, s90
	s_addc_u32 s101, s45, 0
	global_load_lds_dwordx4 v201, s[100:101]
	v_add_u32_e32 v120, s25, v206
	ds_read_b64_tr_b16 v[108:109], v210 offset:60416
	ds_read_b64_tr_b16 v[110:111], v210 offset:60928
	ds_read_b128 v[166:169], v120
	v_exp_f32_e32 v70, v70
	v_exp_f32_e32 v71, v71
	v_mfma_f32_32x32x16_bf16 v[0:15], v[112:115], v[150:153], v[0:15]
	ds_read_b64_tr_b16 v[112:113], v210 offset:64512
	ds_read_b64_tr_b16 v[114:115], v210 offset:65024
	ds_read_b128 v[162:165], v120 offset:4096
	v_exp_f32_e32 v72, v72
	v_exp_f32_e32 v73, v73
	s_waitcnt lgkmcnt(7)
	v_mfma_f32_32x32x16_bf16 v[48:63], v[116:119], v[146:149], v[48:63]
	v_exp_f32_e32 v74, v74
	v_exp_f32_e32 v75, v75
	v_mfma_f32_32x32x16_bf16 v[32:47], v[104:107], v[146:149], v[32:47]
	v_exp_f32_e32 v76, v76
	v_exp_f32_e32 v77, v77
	s_waitcnt lgkmcnt(1)
	v_mfma_f32_32x32x16_bf16 v[16:31], v[108:111], v[146:149], v[16:31]
	s_add_i32 m0, s10, s22
	s_addk_i32 m0, 0x400
	s_add_u32 s100, s100, 0x58000
	s_addc_u32 s101, s101, 0
	global_load_lds_dwordx4 v201, s[100:101]
	v_exp_f32_e32 v78, v78
	v_exp_f32_e32 v79, v79
	v_mfma_f32_32x32x16_bf16 v[0:15], v[112:115], v[146:149], v[0:15]
	s_waitcnt vmcnt(4) lgkmcnt(0)
	s_barrier
	s_cmp_ge_u32 s24, s4
	s_mov_b32 s20, s11
	s_mov_b32 s11, s23
	s_mov_b32 s33, s24
	s_cbranch_scc0 .LBB0_86
	ds_bpermute_b32 v64, v246, v209
	s_waitcnt vmcnt(0)
	s_barrier
	s_cmpk_lt_u32 s17, 0x100
	s_mov_b64 s[10:11], -1
	s_waitcnt lgkmcnt(0)
	v_add_f32_e32 v64, v209, v64
	v_div_scale_f32 v65, s[4:5], v64, v64, 1.0
	v_rcp_f32_e32 v66, v65
	v_div_scale_f32 v67, vcc, 1.0, v64, 1.0
	s_cselect_b64 s[4:5], -1, 0
	v_fma_f32 v68, -v65, v66, 1.0
	v_fmac_f32_e32 v66, v68, v66
	v_mul_f32_e32 v68, v67, v66
	v_fma_f32 v69, -v65, v68, v67
	v_fmac_f32_e32 v68, v69, v66
	v_fma_f32 v65, -v65, v68, v67
	v_div_fmas_f32 v65, v65, v66, v68
	v_div_fixup_f32 v134, v65, v64, 1.0
	s_and_b64 vcc, exec, s[4:5]
	s_cbranch_vccnz .LBB0_89
	s_lshl_b32 s10, s18, 14
	s_add_i32 s10, s10, 0
	v_mul_f32_e32 v64, v48, v134
	v_lshl_add_u32 v65, v202, 2, s10
	v_mul_f32_e32 v66, v49, v134
	ds_write2st64_b32 v65, v64, v66 offset1:1
	v_mul_f32_e32 v64, v50, v134
	v_mul_f32_e32 v66, v51, v134
	ds_write2st64_b32 v65, v64, v66 offset0:2 offset1:3
	v_mul_f32_e32 v64, v52, v134
	v_mul_f32_e32 v66, v53, v134
	ds_write2st64_b32 v65, v64, v66 offset0:4 offset1:5
	v_mul_f32_e32 v64, v54, v134
	v_mul_f32_e32 v66, v55, v134
	ds_write2st64_b32 v65, v64, v66 offset0:6 offset1:7
	v_mul_f32_e32 v64, v56, v134
	v_mul_f32_e32 v66, v57, v134
	ds_write2st64_b32 v65, v64, v66 offset0:8 offset1:9
	v_mul_f32_e32 v64, v58, v134
	v_mul_f32_e32 v66, v59, v134
	ds_write2st64_b32 v65, v64, v66 offset0:10 offset1:11
	v_mul_f32_e32 v64, v60, v134
	v_mul_f32_e32 v66, v61, v134
	ds_write2st64_b32 v65, v64, v66 offset0:12 offset1:13
	v_mul_f32_e32 v64, v62, v134
	v_mul_f32_e32 v66, v63, v134
	ds_write2st64_b32 v65, v64, v66 offset0:14 offset1:15
	v_mul_f32_e32 v64, v32, v134
	v_mul_f32_e32 v66, v33, v134
	ds_write2st64_b32 v65, v64, v66 offset0:16 offset1:17
	v_mul_f32_e32 v64, v34, v134
	v_mul_f32_e32 v66, v35, v134
	ds_write2st64_b32 v65, v64, v66 offset0:18 offset1:19
	v_mul_f32_e32 v64, v36, v134
	v_mul_f32_e32 v66, v37, v134
	ds_write2st64_b32 v65, v64, v66 offset0:20 offset1:21
	v_mul_f32_e32 v64, v38, v134
	v_mul_f32_e32 v66, v39, v134
	ds_write2st64_b32 v65, v64, v66 offset0:22 offset1:23
	v_mul_f32_e32 v64, v40, v134
	v_mul_f32_e32 v66, v41, v134
	ds_write2st64_b32 v65, v64, v66 offset0:24 offset1:25
	v_mul_f32_e32 v64, v42, v134
	v_mul_f32_e32 v66, v43, v134
	ds_write2st64_b32 v65, v64, v66 offset0:26 offset1:27
	v_mul_f32_e32 v64, v44, v134
	v_mul_f32_e32 v66, v45, v134
	ds_write2st64_b32 v65, v64, v66 offset0:28 offset1:29
	v_mul_f32_e32 v64, v46, v134
	v_mul_f32_e32 v66, v47, v134
	ds_write2st64_b32 v65, v64, v66 offset0:30 offset1:31
	v_mul_f32_e32 v64, v16, v134
	v_mul_f32_e32 v66, v17, v134
	ds_write2st64_b32 v65, v64, v66 offset0:32 offset1:33
	v_mul_f32_e32 v64, v18, v134
	v_mul_f32_e32 v66, v19, v134
	ds_write2st64_b32 v65, v64, v66 offset0:34 offset1:35
	v_mul_f32_e32 v64, v20, v134
	v_mul_f32_e32 v66, v21, v134
	ds_write2st64_b32 v65, v64, v66 offset0:36 offset1:37
	v_mul_f32_e32 v64, v22, v134
	v_mul_f32_e32 v66, v23, v134
	ds_write2st64_b32 v65, v64, v66 offset0:38 offset1:39
	v_mul_f32_e32 v64, v24, v134
	v_mul_f32_e32 v66, v25, v134
	ds_write2st64_b32 v65, v64, v66 offset0:40 offset1:41
	v_mul_f32_e32 v64, v26, v134
	v_mul_f32_e32 v66, v27, v134
	ds_write2st64_b32 v65, v64, v66 offset0:42 offset1:43
	v_mul_f32_e32 v64, v28, v134
	v_mul_f32_e32 v66, v29, v134
	ds_write2st64_b32 v65, v64, v66 offset0:44 offset1:45
	v_mul_f32_e32 v64, v30, v134
	v_mul_f32_e32 v66, v31, v134
	ds_write2st64_b32 v65, v64, v66 offset0:46 offset1:47
	v_mul_f32_e32 v64, v0, v134
	v_mul_f32_e32 v66, v1, v134
	ds_write2st64_b32 v65, v64, v66 offset0:48 offset1:49
	v_mul_f32_e32 v64, v2, v134
	v_mul_f32_e32 v66, v3, v134
	ds_write2st64_b32 v65, v64, v66 offset0:50 offset1:51
	v_mul_f32_e32 v64, v4, v134
	v_mul_f32_e32 v66, v5, v134
	ds_write2st64_b32 v65, v64, v66 offset0:52 offset1:53
	v_mul_f32_e32 v64, v6, v134
	v_mul_f32_e32 v66, v7, v134
	ds_write2st64_b32 v65, v64, v66 offset0:54 offset1:55
	v_mul_f32_e32 v64, v8, v134
	v_mul_f32_e32 v66, v9, v134
	ds_write2st64_b32 v65, v64, v66 offset0:56 offset1:57
	v_mul_f32_e32 v64, v10, v134
	v_mul_f32_e32 v66, v11, v134
	ds_write2st64_b32 v65, v64, v66 offset0:58 offset1:59
	v_mul_f32_e32 v64, v12, v134
	v_mul_f32_e32 v66, v13, v134
	ds_write2st64_b32 v65, v64, v66 offset0:60 offset1:61
	v_mul_f32_e32 v64, v14, v134
	v_mul_f32_e32 v66, v15, v134
	s_mov_b64 s[10:11], 0
	ds_write2st64_b32 v65, v64, v66 offset0:62 offset1:63
